# v71 + ssd_s3 unit staging loads (B, C, x rows) issued right after the cumsum loads instead of after its three barriers
# baseline (speedup 1.0000x reference)
; __device__ __forceinline__ void ssd_cumsum(const Params& p, int row0, int g, float* csb, float* dtb) {
;     const int tid = threadIdx.x, hh = tid >> 7, l = tid & 127, h = g * 4 + hh, lane = tid & 63;
;     const float dt = ((const float*)(p.ws + WS_DT))[(size_t)(row0 + l) * 16 + h];
;     const float a = -__expf(p.a_log[h]);
;     float v = dt * a;
; #pragma unroll
;     for (int off = 1; off < 64; off <<= 1) { const float t = __shfl_up(v, off); if (lane >= off) v += t; }
;     dtb[tid] = dt; csb[tid] = v;
;     __syncthreads();
;     if (l >= 64) { v += csb[hh * 128 + 63]; }
;     __syncthreads();
;     csb[tid] = v;
;     __syncthreads();
; }
; __device__ __forceinline__ void ssd_s3_unit(const Params& p, int unit, unsigned char* ldsb) {
;     ...
; #pragma unroll
;     for (int i = 0; i < 4; ++i) {
;         const int e = tid + 512 * i, l = e >> 4, n8 = (e & 15) * 8;
;         *(uint4*)(Bs + l * 136 + n8) = *(const uint4*)(xbc + (size_t)(row0 + l) * 2048 + 1024 + g * 128 + n8);
;         *(uint4*)(Cs + l * 136 + n8) = *(const uint4*)(xbc + (size_t)(row0 + l) * 2048 + 1536 + g * 128 + n8);
;     }
; #pragma unroll
;     for (int i = 0; i < 8; ++i) {
;         const int e = tid + 512 * i, l = e & 127, p8 = (e >> 7) * 8;
;         const uint4 v = *(const uint4*)(xbc + (size_t)(row0 + l) * 2048 + g * 256 + p8);
.LBB0_525:
	v_readlane_b32 s90, v252, 1
	v_readlane_b32 s91, v252, 2
	s_ashr_i32 s6, s87, 7
	s_lshl_b32 s0, s87, 5
	s_lshl_b32 s7, s6, 12
	s_and_b32 s0, s0, 0xf80
	s_or_b32 s21, s0, s7
	s_load_dwordx2 s[88:89], s[90:91], 0xb8
	s_load_dwordx2 s[0:1], s[90:91], 0x50
	s_and_b32 s20, s87, 3
	s_lshl_b32 s8, s20, 2
	v_or_b32_e32 v0, s21, v113
	v_ashrrev_i32_e32 v1, 31, v0
	v_add_lshl_u32 v52, s8, v196, 2
	v_lshlrev_b64 v[2:3], 6, v[0:1]
	s_waitcnt lgkmcnt(0)
	global_load_dword v4, v52, s[0:1]
	v_lshl_add_u64 v[2:3], s[88:89], 0, v[2:3]
	v_lshl_add_u64 v[2:3], v[2:3], 0, v[52:53]
	s_mov_b32 s0, 0x16600000
	v_add_co_u32_e32 v2, vcc, s0, v2
	v_add_u32_e32 v5, -1, v155
	s_nop 0
	v_addc_co_u32_e32 v3, vcc, 0, v3, vcc
	global_load_dword v2, v[2:3], off
	s_add_u32 s10, s88, 0x16800000
	s_addc_u32 s11, s89, 0
	s_lshl_b32 s12, s20, 8
	s_lshl_b32 s14, s20, 9
	v_or_b32_e32 v182, s21, v112
	v_lshlrev_b32_e32 v182, 12, v182
	v_add3_u32 v182, v182, s12, v84
	v_mov_b32_e32 v183, 0
	v_lshl_add_u64 v[182:183], s[10:11], 0, v[182:183]
	global_load_dwordx4 v[182:185], v[182:183], off offset:2048
	v_or_b32_e32 v186, s21, v112
	v_lshlrev_b32_e32 v186, 12, v186
	v_add3_u32 v186, v186, s12, v84
	v_mov_b32_e32 v187, 0
	v_lshl_add_u64 v[186:187], s[10:11], 0, v[186:187]
	global_load_dwordx4 v[186:189], v[186:187], off offset:3072
	v_or_b32_e32 v190, s21, v118
	v_lshlrev_b32_e32 v190, 12, v190
	v_add3_u32 v190, v190, s12, v84
	v_mov_b32_e32 v191, 0
	v_lshl_add_u64 v[190:191], s[10:11], 0, v[190:191]
	global_load_dwordx4 v[190:193], v[190:191], off offset:2048
	v_or_b32_e32 v198, s21, v118
	v_lshlrev_b32_e32 v198, 12, v198
	v_add3_u32 v198, v198, s12, v84
	v_mov_b32_e32 v199, 0
	v_lshl_add_u64 v[198:199], s[10:11], 0, v[198:199]
	global_load_dwordx4 v[198:201], v[198:199], off offset:3072
	v_or_b32_e32 v202, 64, v112
	v_or_b32_e32 v202, s21, v202
	v_lshlrev_b32_e32 v202, 12, v202
	v_add3_u32 v202, v202, s12, v84
	v_mov_b32_e32 v203, 0
	v_lshl_add_u64 v[202:203], s[10:11], 0, v[202:203]
	global_load_dwordx4 v[202:205], v[202:203], off offset:2048
	v_or_b32_e32 v206, 64, v112
	v_or_b32_e32 v206, s21, v206
	v_lshlrev_b32_e32 v206, 12, v206
	v_add3_u32 v206, v206, s12, v84
	v_mov_b32_e32 v207, 0
	v_lshl_add_u64 v[206:207], s[10:11], 0, v[206:207]
	global_load_dwordx4 v[206:209], v[206:207], off offset:3072
	v_add_u32_e32 v210, s21, v120
	v_lshlrev_b32_e32 v210, 12, v210
	v_add3_u32 v210, v210, s12, v84
	v_mov_b32_e32 v211, 0
	v_lshl_add_u64 v[210:211], s[10:11], 0, v[210:211]
	global_load_dwordx4 v[210:213], v[210:211], off offset:2048
	v_add_u32_e32 v214, s21, v120
	v_lshlrev_b32_e32 v214, 12, v214
	v_add3_u32 v214, v214, s12, v84
	v_mov_b32_e32 v215, 0
	v_lshl_add_u64 v[214:215], s[10:11], 0, v[214:215]
	global_load_dwordx4 v[214:217], v[214:215], off offset:3072
	v_or_b32_e32 v218, s21, v113
	v_lshlrev_b32_e32 v218, 12, v218
	v_add3_u32 v218, v218, s14, v86
	v_mov_b32_e32 v219, 0
	v_lshl_add_u64 v[218:219], s[10:11], 0, v[218:219]
	global_load_dwordx4 v[218:221], v[218:219], off
	v_or_b32_e32 v222, s21, v113
	v_lshlrev_b32_e32 v222, 12, v222
	v_add3_u32 v222, v222, s14, v88
	v_mov_b32_e32 v223, 0
	v_lshl_add_u64 v[222:223], s[10:11], 0, v[222:223]
	global_load_dwordx4 v[222:225], v[222:223], off
	v_or_b32_e32 v226, s21, v113
	v_lshlrev_b32_e32 v226, 12, v226
	v_add3_u32 v226, v226, s14, v90
	v_mov_b32_e32 v227, 0
	v_lshl_add_u64 v[226:227], s[10:11], 0, v[226:227]
	global_load_dwordx4 v[226:229], v[226:227], off
	v_or_b32_e32 v230, s21, v113
	v_lshlrev_b32_e32 v230, 12, v230
	v_add3_u32 v230, v230, s14, v92
	v_mov_b32_e32 v231, 0
	v_lshl_add_u64 v[230:231], s[10:11], 0, v[230:231]
	global_load_dwordx4 v[230:233], v[230:231], off
	v_or_b32_e32 v234, s21, v113
	v_lshlrev_b32_e32 v234, 12, v234
	v_add3_u32 v234, v234, s14, v86
	v_mov_b32_e32 v235, 0
	v_lshl_add_u64 v[234:235], s[10:11], 0, v[234:235]
	global_load_dwordx4 v[234:237], v[234:235], off offset:256
	v_or_b32_e32 v238, s21, v113
	v_lshlrev_b32_e32 v238, 12, v238
	v_add3_u32 v238, v238, s14, v94
	v_mov_b32_e32 v239, 0
	v_lshl_add_u64 v[238:239], s[10:11], 0, v[238:239]
	global_load_dwordx4 v[238:241], v[238:239], off
	v_or_b32_e32 v242, s21, v113
	v_lshlrev_b32_e32 v242, 12, v242
	v_add3_u32 v242, v242, s14, v86
	v_mov_b32_e32 v243, 0
	v_lshl_add_u64 v[242:243], s[10:11], 0, v[242:243]
	global_load_dwordx4 v[242:245], v[242:243], off offset:384
	v_or_b32_e32 v246, s21, v113
	v_lshlrev_b32_e32 v246, 12, v246
	v_add3_u32 v246, v246, s14, v96
	v_mov_b32_e32 v247, 0
	v_lshl_add_u64 v[246:247], s[10:11], 0, v[246:247]
	global_load_dwordx4 v[246:249], v[246:247], off
	v_and_b32_e32 v3, 64, v155
	v_cmp_lt_i32_e32 vcc, v5, v3
	v_add_u32_e32 v7, -2, v155
	v_readlane_b32 s0, v252, 12
	v_cndmask_b32_e32 v5, v5, v155, vcc
	v_lshlrev_b32_e32 v5, 2, v5
	v_cmp_lt_i32_e32 vcc, v7, v3
	v_readlane_b32 s1, v252, 13
	s_waitcnt vmcnt(17)
	v_mul_f32_e32 v4, 0x3fb8aa3b, v4
	v_exp_f32_e32 v4, v4
	v_cndmask_b32_e32 v7, v7, v155, vcc
	v_lshlrev_b32_e32 v7, 2, v7
	s_waitcnt vmcnt(16)
	v_mul_f32_e64 v6, v2, -v4
	ds_bpermute_b32 v5, v5, v6
	ds_write_b32 v114, v2
	s_waitcnt lgkmcnt(1)
	v_fma_f32 v4, v2, -v4, v5
	v_cndmask_b32_e64 v4, v4, v6, s[0:1]
	ds_bpermute_b32 v5, v7, v4
	v_add_u32_e32 v6, -4, v155
	v_cmp_lt_i32_e32 vcc, v6, v3
	v_readlane_b32 s0, v252, 14
	v_readlane_b32 s1, v252, 15
	v_cndmask_b32_e32 v6, v6, v155, vcc
	s_waitcnt lgkmcnt(0)
	v_add_f32_e32 v5, v4, v5
	v_lshlrev_b32_e32 v6, 2, v6
	v_cndmask_b32_e64 v4, v5, v4, s[0:1]
	ds_bpermute_b32 v5, v6, v4
	v_add_u32_e32 v6, -8, v155
	v_cmp_lt_i32_e32 vcc, v6, v3
	v_readlane_b32 s0, v252, 16
	v_readlane_b32 s1, v252, 17
	v_cndmask_b32_e32 v6, v6, v155, vcc
	s_waitcnt lgkmcnt(0)
	v_add_f32_e32 v5, v4, v5
	v_lshlrev_b32_e32 v6, 2, v6
	v_cndmask_b32_e64 v4, v5, v4, s[0:1]
	ds_bpermute_b32 v5, v6, v4
	v_add_u32_e32 v6, -16, v155
	v_cmp_lt_i32_e32 vcc, v6, v3
	v_readlane_b32 s0, v252, 18
	v_readlane_b32 s1, v252, 19
	v_cndmask_b32_e32 v6, v6, v155, vcc
	s_waitcnt lgkmcnt(0)
	v_add_f32_e32 v5, v4, v5
	v_lshlrev_b32_e32 v6, 2, v6
	v_cndmask_b32_e64 v4, v5, v4, s[0:1]
	ds_bpermute_b32 v5, v6, v4
	v_subrev_u32_e32 v6, 32, v155
	v_cmp_lt_i32_e32 vcc, v6, v3
	v_readlane_b32 s0, v252, 20
	v_readlane_b32 s1, v252, 21
	v_cndmask_b32_e32 v3, v6, v155, vcc
	s_waitcnt lgkmcnt(0)
	v_add_f32_e32 v5, v4, v5
	v_lshlrev_b32_e32 v3, 2, v3
	v_cndmask_b32_e64 v4, v5, v4, s[0:1]
	ds_bpermute_b32 v3, v3, v4
	v_readfirstlane_b32 vcc_lo, v172
	s_waitcnt lgkmcnt(0)
	v_add_f32_e32 v2, v4, v3
	v_cndmask_b32_e64 v2, v2, v4, s[16:17]
	ds_write_b32 v115, v2
	s_waitcnt lgkmcnt(0)
	s_barrier
	s_and_saveexec_b64 s[0:1], s[18:19]
	s_cbranch_execz .LBB0_527
	ds_read_b32 v3, v116 offset:252
	s_waitcnt lgkmcnt(0)
	v_add_f32_e32 v2, v2, v3
; __device__ __forceinline__ void ssd_cumsum(const Params& p, int row0, int g, float* csb, float* dtb) {
;     ...
;     if (l >= 64) { v += csb[hh * 128 + 63]; }
;     __syncthreads();
;     csb[tid] = v;
;     __syncthreads();
; }
; __device__ __forceinline__ void ssd_s3_unit(const Params& p, int unit, unsigned char* ldsb) {
;     ...
; #pragma unroll
;     for (int i = 0; i < 4; ++i) {
;         const int e = tid + 512 * i, l = e >> 4, n8 = (e & 15) * 8;
;         *(uint4*)(Bs + l * 136 + n8) = *(const uint4*)(xbc + (size_t)(row0 + l) * 2048 + 1024 + g * 128 + n8);
;         *(uint4*)(Cs + l * 136 + n8) = *(const uint4*)(xbc + (size_t)(row0 + l) * 2048 + 1536 + g * 128 + n8);
;     }
; #pragma unroll
;     for (int i = 0; i < 8; ++i) {
;         const int e = tid + 512 * i, l = e & 127, p8 = (e >> 7) * 8;
;         const uint4 v = *(const uint4*)(xbc + (size_t)(row0 + l) * 2048 + g * 256 + p8);
.LBB0_527:
	s_or_b64 exec, exec, s[0:1]
	v_or_b32_e32 v18, 64, v112
	s_barrier
	ds_write_b32 v115, v2
	v_or_b32_e32 v2, s21, v112
	v_or_b32_e32 v10, s21, v118
	v_or_b32_e32 v18, s21, v18
	v_add_u32_e32 v26, s21, v120
	s_add_u32 s0, s88, 0x16800000
	v_ashrrev_i32_e32 v3, 31, v2
	v_ashrrev_i32_e32 v11, 31, v10
	v_ashrrev_i32_e32 v19, 31, v18
	v_ashrrev_i32_e32 v27, 31, v26
	s_addc_u32 s1, s89, 0
	v_lshlrev_b64 v[2:3], 12, v[2:3]
	v_lshlrev_b64 v[10:11], 12, v[10:11]
	v_lshlrev_b64 v[18:19], 12, v[18:19]
	v_lshlrev_b64 v[26:27], 12, v[26:27]
	v_lshl_add_u64 v[2:3], s[0:1], 0, v[2:3]
	s_lshl_b32 s96, s20, 8
	v_lshl_add_u64 v[10:11], s[0:1], 0, v[10:11]
	v_lshl_add_u64 v[18:19], s[0:1], 0, v[18:19]
	v_lshl_add_u64 v[26:27], s[0:1], 0, v[26:27]
	v_lshlrev_b64 v[0:1], 12, v[0:1]
	v_lshl_add_u64 v[2:3], v[2:3], 0, s[96:97]
	v_lshl_add_u64 v[10:11], v[10:11], 0, s[96:97]
	v_lshl_add_u64 v[18:19], v[18:19], 0, s[96:97]
	v_lshl_add_u64 v[26:27], v[26:27], 0, s[96:97]
	v_lshl_add_u64 v[0:1], s[0:1], 0, v[0:1]
	s_lshl_b32 s96, s20, 9
	v_mov_b32_e32 v85, v53
	v_lshl_add_u64 v[0:1], v[0:1], 0, s[96:97]
	v_mov_b32_e32 v87, v53
	v_mov_b32_e32 v89, v53
	v_mov_b32_e32 v91, v53
	v_mov_b32_e32 v93, v53
	v_mov_b32_e32 v95, v53
	v_lshl_add_u64 v[6:7], v[2:3], 0, v[84:85]
	v_lshl_add_u64 v[14:15], v[10:11], 0, v[84:85]
	v_lshl_add_u64 v[22:23], v[18:19], 0, v[84:85]
	v_lshl_add_u64 v[30:31], v[26:27], 0, v[84:85]
	v_lshl_add_u64 v[50:51], v[0:1], 0, v[86:87]
	v_lshl_add_u64 v[38:39], v[0:1], 0, v[88:89]
	v_lshl_add_u64 v[42:43], v[0:1], 0, v[90:91]
	v_lshl_add_u64 v[46:47], v[0:1], 0, v[92:93]
	v_lshl_add_u64 v[102:103], v[0:1], 0, v[94:95]
	s_waitcnt lgkmcnt(0)
	s_barrier
; #define MFMA16(a, b, c) __builtin_amdgcn_mfma_f32_16x16x32_bf16((a), (b), (c), 0, 0, 0)
; __device__ __forceinline__ void ssd_s3_unit(const Params& p, int unit, unsigned char* ldsb) {
;     ...
; #pragma unroll
;     for (int i = 0; i < 4; ++i) {
;         const int e = tid + 512 * i, l = e >> 4, n8 = (e & 15) * 8;
;         *(uint4*)(Bs + l * 136 + n8) = *(const uint4*)(xbc + (size_t)(row0 + l) * 2048 + 1024 + g * 128 + n8);
;         *(uint4*)(Cs + l * 136 + n8) = *(const uint4*)(xbc + (size_t)(row0 + l) * 2048 + 1536 + g * 128 + n8);
;     }
; #pragma unroll
;     for (int i = 0; i < 8; ++i) {
;         const int e = tid + 512 * i, l = e & 127, p8 = (e >> 7) * 8;
;         const uint4 v = *(const uint4*)(xbc + (size_t)(row0 + l) * 2048 + g * 256 + p8);
;         bfu* tp = XT4 + p8 * 136 + l;
;         tp[0] = (bfu)(v.x & 0xffff); tp[136] = (bfu)(v.x >> 16); tp[2 * 136] = (bfu)(v.y & 0xffff); tp[3 * 136] = (bfu)(v.y >> 16);
;         tp[4 * 136] = (bfu)(v.z & 0xffff); tp[5 * 136] = (bfu)(v.z >> 16); tp[6 * 136] = (bfu)(v.w & 0xffff); tp[7 * 136] = (bfu)(v.w >> 16);
;     }
;     __syncthreads();
;     f32x4 cbt[8];
; #pragma unroll
;     for (int st = 0; st < 8; ++st) {
;         f32x4 a = {0.f, 0.f, 0.f, 0.f};
;         if (st <= wave) {
; #pragma unroll
;             for (int ks = 0; ks < 4; ++ks)
;                 a = MFMA16(*(const bf16x8*)(Bs + (st * 16 + l15) * 136 + ks * 32 + quad * 8), *(const bf16x8*)(Cs + (wave * 16 + l15) * 136 + ks * 32 + quad * 8), a);
;         }
;         cbt[st] = a;
;     }
	s_waitcnt vmcnt(0)
	v_mov_b64_e32 v[2:3], v[182:183]
	v_mov_b64_e32 v[4:5], v[184:185]
	s_nop 0
	v_mov_b64_e32 v[6:7], v[186:187]
	v_mov_b64_e32 v[8:9], v[188:189]
	s_nop 0
	v_mov_b64_e32 v[10:11], v[190:191]
	v_mov_b64_e32 v[12:13], v[192:193]
	s_nop 0
	v_mov_b64_e32 v[14:15], v[198:199]
	v_mov_b64_e32 v[16:17], v[200:201]
	s_nop 0
	v_mov_b64_e32 v[18:19], v[202:203]
	v_mov_b64_e32 v[20:21], v[204:205]
	s_nop 0
	v_mov_b64_e32 v[22:23], v[206:207]
	v_mov_b64_e32 v[24:25], v[208:209]
	s_nop 0
	v_mov_b64_e32 v[26:27], v[210:211]
	v_mov_b64_e32 v[28:29], v[212:213]
	s_nop 0
	v_mov_b64_e32 v[30:31], v[214:215]
	v_mov_b64_e32 v[32:33], v[216:217]
	v_mov_b32_e32 v97, v53
	v_mov_b64_e32 v[34:35], v[218:219]
	v_mov_b64_e32 v[36:37], v[220:221]
	v_lshl_add_u64 v[0:1], v[0:1], 0, v[96:97]
	v_mov_b64_e32 v[38:39], v[222:223]
	v_mov_b64_e32 v[40:41], v[224:225]
	v_add_u32_e32 v52, 0x8800, v121
	v_mov_b64_e32 v[42:43], v[226:227]
	v_mov_b64_e32 v[44:45], v[228:229]
	s_nop 0
	v_mov_b64_e32 v[46:47], v[230:231]
	v_mov_b64_e32 v[48:49], v[232:233]
	s_nop 0
	v_mov_b64_e32 v[98:99], v[234:235]
	v_mov_b64_e32 v[100:101], v[236:237]
	s_nop 0
	v_mov_b64_e32 v[102:103], v[238:239]
	v_mov_b64_e32 v[104:105], v[240:241]
	s_nop 0
	v_mov_b64_e32 v[106:107], v[242:243]
	v_mov_b64_e32 v[108:109], v[244:245]
	v_mov_b64_e32 v[164:165], v[246:247]
	v_mov_b64_e32 v[166:167], v[248:249]
	v_add_u32_e32 v0, 0x8800, v117
	v_add_u32_e32 v1, 0x8800, v119
	v_add_u32_e32 v50, 0xcc00, v117
	v_add_u32_e32 v51, 0x4400, v117
	s_lshr_b32 s0, vcc_lo, 2
	s_and_b32 vcc_hi, s0, 0x3ffffff0
	s_movk_i32 s0, 0x110
	s_cmp_lt_u32 vcc_lo, 64
	s_waitcnt vmcnt(15)
	ds_write_b128 v0, v[2:5]
	s_waitcnt vmcnt(14)
	ds_write_b128 v117, v[6:9]
	s_waitcnt vmcnt(13)
	ds_write_b128 v1, v[10:13]
	s_waitcnt vmcnt(12)
	ds_write_b128 v119, v[14:17]
	s_waitcnt vmcnt(11)
	ds_write_b128 v50, v[18:21]
	s_waitcnt vmcnt(10)
	ds_write_b128 v51, v[22:25]
	s_waitcnt vmcnt(9)
	ds_write_b128 v52, v[26:29]
	s_waitcnt vmcnt(8)
	ds_write_b128 v121, v[30:33]
	s_waitcnt vmcnt(7)
	ds_write_b16 v156, v34
	ds_write_b16_d16_hi v156, v34 offset:272
	ds_write_b16 v156, v35 offset:544
	ds_write_b16_d16_hi v156, v35 offset:816
	ds_write_b16 v156, v36 offset:1088
	ds_write_b16_d16_hi v156, v36 offset:1360
	ds_write_b16 v156, v37 offset:1632
	ds_write_b16_d16_hi v156, v37 offset:1904
	s_waitcnt vmcnt(6)
	ds_write_b16 v157, v38
	ds_write_b16_d16_hi v157, v38 offset:272
	ds_write_b16 v157, v39 offset:544
	ds_write_b16_d16_hi v157, v39 offset:816
	ds_write_b16 v157, v40 offset:1088
	ds_write_b16_d16_hi v157, v40 offset:1360
	ds_write_b16 v157, v41 offset:1632
	ds_write_b16_d16_hi v157, v41 offset:1904
	s_waitcnt vmcnt(5)
	ds_write_b16 v158, v42
	ds_write_b16_d16_hi v158, v42 offset:272
	ds_write_b16 v158, v43 offset:544
	ds_write_b16_d16_hi v158, v43 offset:816
	ds_write_b16 v158, v44 offset:1088
	ds_write_b16_d16_hi v158, v44 offset:1360
	ds_write_b16 v158, v45 offset:1632
	ds_write_b16_d16_hi v158, v45 offset:1904
	s_waitcnt vmcnt(4)
	ds_write_b16 v159, v46
	ds_write_b16_d16_hi v159, v46 offset:272
	ds_write_b16 v159, v47 offset:544
	ds_write_b16_d16_hi v159, v47 offset:816
	ds_write_b16 v159, v48 offset:1088
	ds_write_b16_d16_hi v159, v48 offset:1360
	ds_write_b16 v159, v49 offset:1632
	ds_write_b16_d16_hi v159, v49 offset:1904
	s_waitcnt vmcnt(3)
	ds_write_b16 v156, v98 offset:34816
	ds_write_b16_d16_hi v156, v98 offset:35088
	ds_write_b16 v156, v99 offset:35360
	ds_write_b16_d16_hi v156, v99 offset:35632
	ds_write_b16 v156, v100 offset:35904
	ds_write_b16_d16_hi v156, v100 offset:36176
	ds_write_b16 v156, v101 offset:36448
	ds_write_b16_d16_hi v156, v101 offset:36720
	s_waitcnt vmcnt(2)
	ds_write_b16 v160, v102
	ds_write_b16_d16_hi v160, v102 offset:272
	ds_write_b16 v160, v103 offset:544
	ds_write_b16_d16_hi v160, v103 offset:816
	ds_write_b16 v160, v104 offset:1088
	ds_write_b16_d16_hi v160, v104 offset:1360
	ds_write_b16 v160, v105 offset:1632
	ds_write_b16_d16_hi v160, v105 offset:1904
	s_waitcnt vmcnt(1)
	ds_write_b16 v156, v106 offset:52224
	ds_write_b16_d16_hi v156, v106 offset:52496
	ds_write_b16 v156, v107 offset:52768
	ds_write_b16_d16_hi v156, v107 offset:53040
	ds_write_b16 v156, v108 offset:53312
	ds_write_b16_d16_hi v156, v108 offset:53584
	ds_write_b16 v156, v109 offset:53856
	ds_write_b16_d16_hi v156, v109 offset:54128
	s_waitcnt vmcnt(0)
	ds_write_b16 v161, v164
	ds_write_b16_d16_hi v161, v164 offset:272
	ds_write_b16 v161, v165 offset:544
	ds_write_b16_d16_hi v161, v165 offset:816
	ds_write_b16 v161, v166 offset:1088
	ds_write_b16_d16_hi v161, v166 offset:1360
	ds_write_b16 v161, v167 offset:1632
	ds_write_b16_d16_hi v161, v167 offset:1904
	s_waitcnt lgkmcnt(0)
	s_barrier
	ds_read_b128 v[0:3], v162 offset:34816
	v_or_b32_e32 v48, vcc_hi, v174
	v_mul_lo_u32 v4, v48, s0
	v_add_u32_e32 v85, 0, v4
	v_lshl_add_u32 v12, v195, 1, v85
	ds_read_b128 v[4:7], v162 offset:34880
	ds_read_b128 v[36:39], v12
	ds_read_b128 v[32:35], v12 offset:64
	ds_read_b128 v[8:11], v162 offset:34944
	s_waitcnt lgkmcnt(2)
	v_mfma_f32_16x16x32_bf16 v[0:3], v[0:3], v[36:39], 0
	s_waitcnt lgkmcnt(1)
	v_mfma_f32_16x16x32_bf16 v[0:3], v[4:7], v[32:35], v[0:3]
	ds_read_b128 v[4:7], v162 offset:35008
	ds_read_b128 v[40:43], v12 offset:128
	ds_read_b128 v[44:47], v12 offset:192
	s_waitcnt lgkmcnt(1)
	v_mfma_f32_16x16x32_bf16 v[0:3], v[8:11], v[40:43], v[0:3]
	v_mov_b32_e32 v8, 0
	v_mov_b32_e32 v9, 0
	v_mov_b32_e32 v10, 0
	s_waitcnt lgkmcnt(0)
	v_mfma_f32_16x16x32_bf16 v[0:3], v[4:7], v[44:47], v[0:3]
	v_mov_b32_e32 v4, 0
	v_mov_b32_e32 v11, 0
	s_cbranch_scc1 .LBB0_529
	ds_read_b128 v[6:9], v162 offset:39168
	ds_read_b128 v[10:13], v162 offset:39232
	ds_read_b128 v[14:17], v162 offset:39296
	s_waitcnt lgkmcnt(2)
	v_mfma_f32_16x16x32_bf16 v[6:9], v[6:9], v[36:39], 0
	s_waitcnt lgkmcnt(1)
	v_mfma_f32_16x16x32_bf16 v[6:9], v[10:13], v[32:35], v[6:9]
	ds_read_b128 v[10:13], v162 offset:39360
	s_waitcnt lgkmcnt(1)
	v_mfma_f32_16x16x32_bf16 v[6:9], v[14:17], v[40:43], v[6:9]
	s_waitcnt lgkmcnt(0)
	v_mfma_f32_16x16x32_bf16 v[8:11], v[10:13], v[44:47], v[6:9]
